# mLSTM chunk segment 3: per-tile LDS fragments read up front, MFMAs issued as data lands (Q.C^T, W.V^T, Kw^T.V^T), same math
# speedup vs baseline: 1.0326x; 1.0007x over previous
.LBB0_249:
	s_or_b64 exec, exec, s[46:47]
	s_waitcnt lgkmcnt(0)
	s_barrier
	ds_read_b128 v[210:213], v87 offset:53248
	ds_read_b128 v[218:221], v128 offset:62464
	ds_read_b128 v[214:217], v87 offset:53312
	ds_read_b128 v[222:225], v128 offset:62528
	ds_read_b128 v[226:229], v147 offset:62464
	ds_read_b128 v[230:233], v147 offset:62528
	ds_read_b128 v[234:237], v131
	ds_read_b32 v238, v129
	ds_read_b32 v239, v148
	v_add_u32_e32 v0, v89, v153
	s_waitcnt lgkmcnt(7)
	v_mfma_f32_16x16x32_bf16 v[60:63], v[210:213], v[218:221], 0
	s_waitcnt lgkmcnt(5)
	v_mfma_f32_16x16x32_bf16 v[60:63], v[214:217], v[222:225], v[60:63]
	s_waitcnt lgkmcnt(4)
	v_mfma_f32_16x16x32_bf16 v[112:115], v[210:213], v[226:229], 0
	s_waitcnt lgkmcnt(3)
	v_mfma_f32_16x16x32_bf16 v[112:115], v[214:217], v[230:233], v[112:115]
	ds_read2st64_b32 v[2:3], v0 offset0:64 offset1:65
	ds_read2st64_b32 v[206:207], v0 offset0:66 offset1:67
	ds_read2st64_b32 v[208:209], v0 offset0:68 offset1:69
	ds_read2st64_b32 v[120:121], v0 offset0:70 offset1:71
	ds_read_b128 v[218:221], v154
	ds_read_b128 v[222:225], v155
	s_waitcnt lgkmcnt(6)
	v_add_f32_e32 v116, v234, v238
	v_add_f32_e32 v117, v235, v238
	v_add_f32_e32 v118, v236, v238
	v_add_f32_e32 v119, v237, v238
	v_add_f32_e32 v240, v234, v239
	v_add_f32_e32 v241, v235, v239
	v_add_f32_e32 v242, v236, v239
	v_add_f32_e32 v243, v237, v239
	v_mul_f32_e32 v116, 0x3fb8aa3b, v116
	v_mul_f32_e32 v117, 0x3fb8aa3b, v117
	v_mul_f32_e32 v118, 0x3fb8aa3b, v118
	v_mul_f32_e32 v119, 0x3fb8aa3b, v119
	v_mul_f32_e32 v240, 0x3fb8aa3b, v240
	v_mul_f32_e32 v241, 0x3fb8aa3b, v241
	v_mul_f32_e32 v242, 0x3fb8aa3b, v242
	v_mul_f32_e32 v243, 0x3fb8aa3b, v243
	v_exp_f32_e32 v116, v116
	v_exp_f32_e32 v117, v117
	v_exp_f32_e32 v118, v118
	v_exp_f32_e32 v119, v119
	v_exp_f32_e32 v240, v240
	v_exp_f32_e32 v241, v241
	v_exp_f32_e32 v242, v242
	v_exp_f32_e32 v243, v243
	v_mul_f32_e32 v116, v60, v116
	v_mul_f32_e32 v117, v61, v117
	v_mul_f32_e32 v118, v62, v118
	v_mul_f32_e32 v119, v63, v119
	v_mul_f32_e32 v240, v112, v240
	v_mul_f32_e32 v241, v113, v241
	v_mul_f32_e32 v242, v114, v242
	v_mul_f32_e32 v243, v115, v243
	v_cndmask_b32_e64 v116, 0, v116, s[20:21]
	v_cndmask_b32_e64 v117, 0, v117, s[22:23]
	v_cndmask_b32_e64 v118, 0, v118, s[24:25]
	v_cndmask_b32_e64 v119, 0, v119, s[26:27]
	v_cndmask_b32_e64 v240, 0, v240, s[28:29]
	v_cndmask_b32_e64 v241, 0, v241, s[30:31]
	v_cndmask_b32_e64 v242, 0, v242, s[34:35]
	v_cndmask_b32_e64 v243, 0, v243, s[36:37]
	v_cvt_pk_bf16_f32 v116, v116, v117
	v_cvt_pk_bf16_f32 v118, v118, v119
	v_cvt_pk_bf16_f32 v240, v240, v241
	v_cvt_pk_bf16_f32 v242, v242, v243
	v_add_u32_e32 v226, v130, v132
	v_add_u32_e32 v227, v130, v134
	v_add_u32_e32 v228, v130, v136
	v_add_u32_e32 v229, v130, v146
	s_waitcnt lgkmcnt(0)
	v_pk_mul_f32 v[2:3], v[2:3], v[218:219]
	v_pk_mul_f32 v[206:207], v[206:207], v[220:221]
	v_pk_mul_f32 v[208:209], v[208:209], v[222:223]
	v_pk_mul_f32 v[120:121], v[120:121], v[224:225]
	ds_write_b16 v226, v116
	ds_write_b16_d16_hi v227, v116
	ds_write_b16 v228, v118
	ds_write_b16_d16_hi v229, v118
	ds_write_b16 v149, v240
	ds_write_b16_d16_hi v150, v240
	ds_write_b16 v151, v242
	ds_write_b16_d16_hi v152, v242
	v_cvt_pk_bf16_f32 v230, v2, v3
	v_cvt_pk_bf16_f32 v231, v206, v207
	v_cvt_pk_bf16_f32 v232, v208, v209
	v_cvt_pk_bf16_f32 v233, v120, v121
	ds_write_b128 v196, v[230:233]
	v_mov_b32_e32 v0, s71
	s_waitcnt lgkmcnt(0)
	s_barrier
	ds_read_b32 v2, v0
	s_and_saveexec_b64 s[46:47], s[38:39]
	s_cbranch_execz .LBB0_267
	ds_read_b128 v[112:115], v156 offset:53248
	ds_read_b128 v[116:119], v157
	ds_read_b128 v[210:213], v156 offset:53312
	ds_read_b128 v[214:217], v157 offset:64
	ds_read_b128 v[218:221], v176
	ds_read_b128 v[222:225], v175
	ds_read_b128 v[234:237], v158
	ds_read_b128 v[238:241], v159
	ds_read_b128 v[230:233], v175 offset:64
	ds_read_b128 v[226:229], v176 offset:64
	v_add_u32_e32 v0, 0xa000, v197
	s_waitcnt lgkmcnt(10)
	v_mov_b32_e32 v3, v2
	v_pk_mul_f32 v[52:53], v[52:53], v[2:3]
	v_pk_mul_f32 v[54:55], v[54:55], v[2:3]
	s_waitcnt lgkmcnt(8)
	v_mfma_f32_16x16x32_bf16 v[60:63], v[112:115], v[116:119], 0
	s_waitcnt lgkmcnt(6)
	v_mfma_f32_16x16x32_bf16 v[60:63], v[210:213], v[214:217], v[60:63]
	ds_read_b128 v[112:115], v159 offset:64
	s_waitcnt lgkmcnt(5)
	v_mfma_f32_16x16x32_bf16 v[52:55], v[218:221], v[222:225], v[52:55]
	s_waitcnt lgkmcnt(4)
	s_nop 6
	v_pk_mul_f32 v[62:63], v[62:63], v[236:237]
	v_pk_mul_f32 v[60:61], v[60:61], v[234:235]
	s_waitcnt lgkmcnt(3)
	v_mfma_f32_16x16x32_bf16 v[60:63], v[238:241], v[222:225], v[60:63]
	s_waitcnt lgkmcnt(0)
	v_mfma_f32_16x16x32_bf16 v[60:63], v[112:115], v[230:233], v[60:63]
	v_mfma_f32_16x16x32_bf16 v[52:55], v[226:229], v[230:233], v[52:55]
	s_nop 7
	ds_write2_b32 v0, v60, v61 offset1:48
	ds_write2_b32 v0, v62, v63 offset0:96 offset1:144
.LBB0_267:
	s_or_b64 exec, exec, s[46:47]
	s_and_saveexec_b64 s[46:47], s[40:41]
	s_cbranch_execz .LBB0_269
	ds_read_b128 v[112:115], v177 offset:53248
	ds_read_b128 v[116:119], v178
	ds_read_b128 v[210:213], v177 offset:53312
	ds_read_b128 v[214:217], v178 offset:64
	ds_read_b128 v[218:221], v182
	ds_read_b128 v[222:225], v181
	ds_read_b128 v[234:237], v179
	ds_read_b128 v[238:241], v180
	ds_read_b128 v[230:233], v181 offset:64
	ds_read_b128 v[226:229], v182 offset:64
	v_add_u32_e32 v0, 0xa000, v198
	s_waitcnt lgkmcnt(10)
	v_mov_b32_e32 v3, v2
	v_pk_mul_f32 v[56:57], v[56:57], v[2:3]
	v_pk_mul_f32 v[58:59], v[58:59], v[2:3]
	s_waitcnt lgkmcnt(8)
	v_mfma_f32_16x16x32_bf16 v[60:63], v[112:115], v[116:119], 0
	s_waitcnt lgkmcnt(6)
	v_mfma_f32_16x16x32_bf16 v[60:63], v[210:213], v[214:217], v[60:63]
	ds_read_b128 v[112:115], v180 offset:64
	s_waitcnt lgkmcnt(5)
	v_mfma_f32_16x16x32_bf16 v[56:59], v[218:221], v[222:225], v[56:59]
	s_waitcnt lgkmcnt(4)
	s_nop 6
	v_pk_mul_f32 v[62:63], v[62:63], v[236:237]
	v_pk_mul_f32 v[60:61], v[60:61], v[234:235]
	s_waitcnt lgkmcnt(3)
	v_mfma_f32_16x16x32_bf16 v[60:63], v[238:241], v[222:225], v[60:63]
	s_waitcnt lgkmcnt(0)
	v_mfma_f32_16x16x32_bf16 v[60:63], v[112:115], v[230:233], v[60:63]
	v_mfma_f32_16x16x32_bf16 v[56:59], v[226:229], v[230:233], v[56:59]
	s_nop 7
	ds_write2_b32 v0, v60, v61 offset1:48
	ds_write2_b32 v0, v62, v63 offset0:96 offset1:144
.LBB0_269:
	s_or_b64 exec, exec, s[46:47]
	s_waitcnt lgkmcnt(0)
	s_barrier
	s_and_saveexec_b64 s[46:47], s[38:39]
	s_nop 1
	v_cvt_pk_bf16_f32 v2, v52, v53
	v_cvt_pk_bf16_f32 v3, v54, v55
	ds_write_b64 v199, v[2:3]
	s_or_b64 exec, exec, s[46:47]
	s_and_saveexec_b64 s[46:47], s[40:41]
	s_cbranch_execz .LBB0_230
	v_cvt_pk_bf16_f32 v2, v56, v57
	v_cvt_pk_bf16_f32 v3, v58, v59
	ds_write_b64 v200, v[2:3]
	s_branch .LBB0_230
